# v019 + mix: first gu-load wait moved after the MFMA section; attention: all-done flags read with two 16-byte LDS reads instead of eight serialized dword reads
# speedup vs baseline: 1.0137x; 1.0018x over previous
; __device__ __forceinline__ void attn_phase(const Params& p, LAS unsigned char* lds, int cidx) {
;     ...
;             __syncthreads();
;             {
;                 int alld = 1;
; #pragma unroll
;                 for (int w = 0; w < 8; ++w) alld &= misc[8 + w];
;                 if (alld) break;
;             }
; #pragma unroll
;             for (int i = 0; i < 2; ++i) {
;                 const int cid = tid + 512 * i, key = cid >> 4, d8 = (cid & 15) * 8;
;                 u32x4 kwv, vwv;
;                 if (!smp) { kwv = __builtin_bit_cast(u32x4, pf[i][0]); vwv = __builtin_bit_cast(u32x4, pf[i][2]); }
.LBB0_633:
	s_waitcnt lgkmcnt(0)
	s_barrier
	ds_read_b128 v[34:37], v0 offset:34848
	ds_read_b128 v[38:41], v0 offset:34864
	s_mov_b64 s[22:23], -1
	s_waitcnt lgkmcnt(1)
	v_and_b32_e32 v1, v34, v35
	v_and_b32_e32 v34, v36, v37
	v_and_b32_e32 v1, v1, v34
	s_waitcnt lgkmcnt(0)
	v_and_b32_e32 v34, v38, v39
	v_and_b32_e32 v35, v40, v41
	v_and_b32_e32 v1, v1, v34
	v_and_b32_e32 v1, v1, v35
	v_and_b32_e32 v1, 1, v1
	v_cmp_eq_u32_e32 vcc, 1, v1
	s_cbranch_vccnz .LBB0_631
	s_cmp_lg_u32 s33, 16
	v_cndmask_b32_e64 v1, 0, 1, s[2:3]
	s_cselect_b64 s[22:23], -1, 0
	v_cmp_ne_u32_e64 s[18:19], 1, v1
	s_andn2_b64 vcc, exec, s[2:3]
	s_mov_b64 s[24:25], -1
	s_cbranch_vccnz .LBB0_636
	s_mov_b64 s[24:25], 0
	s_waitcnt vmcnt(1)
	v_mov_b32_e32 v37, v5
	v_mov_b32_e32 v36, v4
	v_mov_b32_e32 v35, v3
	v_mov_b32_e32 v34, v2
	s_waitcnt vmcnt(0)
	v_mov_b32_e32 v41, v13
	v_mov_b32_e32 v40, v12
	v_mov_b32_e32 v39, v11
	v_mov_b32_e32 v38, v10
